# POOLP (pool mixer) rewritten by hand: blocks of 4 consecutive rows per wave share window taps (26 row loads per 4 outputs instead of 80), same f32 tap order
# baseline (speedup 1.0000x reference)
.LBB0_239:
	s_and_b64 vcc, exec, s[0:1]
	s_cbranch_vccz .LBB0_245
	s_cmp_eq_u32 s52, 6
	s_mov_b64 s[24:25], -1
	s_cbranch_scc0 .LBB0_245
	s_mov_b32 s2, s36
	s_cmp_gt_i32 s36, 0x9fff
	s_cbranch_scc1 .LBB0_244
	v_lshlrev_b32_e32 v2, 4, v182
	v_cmp_lt_u32_e64 s[34:35], 31, v182
	v_readlane_b32 s28, v253, 53
	v_readlane_b32 s29, v253, 54
	v_cndmask_b32_e64 v3, 0, 1.0, s[34:35]
	s_mov_b32 s8, s36
.Lpool_blk:
	s_lshl_b32 s22, s8, 2
	s_cmpk_lt_i32 s22, 0x2000
	s_cbranch_scc0 .Lpool_lat
	s_and_b32 s23, s22, 0xffffff00
	s_and_b32 s24, s22, 0xff
	s_movk_i32 s25, 0x100
	s_branch .Lpool_go
.Lpool_lat:
	s_sub_i32 s0, s22, 0x2000
	s_and_b32 s23, s0, 0xfffff000
	s_add_i32 s23, s23, 0x2000
	s_and_b32 s24, s0, 0xfff
	s_movk_i32 s25, 0x1000
.Lpool_go:
	s_add_i32 s26, s25, -1
	s_add_i32 s0, s24, -8
	s_max_i32 s0, s0, 0
	s_min_i32 s0, s0, s26
	s_add_i32 s0, s0, s23
	s_lshl_b32 s0, s0, 11
	s_add_u32 s6, s28, s0
	s_addc_u32 s7, s29, 0
	global_load_dwordx4 v[4:7], v2, s[6:7] offset:1024
	s_add_i32 s0, s24, -7
	s_max_i32 s0, s0, 0
	s_min_i32 s0, s0, s26
	s_add_i32 s0, s0, s23
	s_lshl_b32 s0, s0, 11
	s_add_u32 s6, s28, s0
	s_addc_u32 s7, s29, 0
	global_load_dwordx4 v[8:11], v2, s[6:7] offset:1024
	s_add_i32 s0, s24, -6
	s_max_i32 s0, s0, 0
	s_min_i32 s0, s0, s26
	s_add_i32 s0, s0, s23
	s_lshl_b32 s0, s0, 11
	s_add_u32 s6, s28, s0
	s_addc_u32 s7, s29, 0
	global_load_dwordx4 v[12:15], v2, s[6:7] offset:1024
	s_add_i32 s0, s24, -5
	s_max_i32 s0, s0, 0
	s_min_i32 s0, s0, s26
	s_add_i32 s0, s0, s23
	s_lshl_b32 s0, s0, 11
	s_add_u32 s6, s28, s0
	s_addc_u32 s7, s29, 0
	global_load_dwordx4 v[16:19], v2, s[6:7] offset:1024
	s_add_i32 s0, s24, -4
	s_max_i32 s0, s0, 0
	s_min_i32 s0, s0, s26
	s_add_i32 s0, s0, s23
	s_lshl_b32 s0, s0, 11
	s_add_u32 s6, s28, s0
	s_addc_u32 s7, s29, 0
	global_load_dwordx4 v[20:23], v2, s[6:7] offset:1024
	s_add_i32 s0, s24, -3
	s_max_i32 s0, s0, 0
	s_min_i32 s0, s0, s26
	s_add_i32 s0, s0, s23
	s_lshl_b32 s0, s0, 11
	s_add_u32 s6, s28, s0
	s_addc_u32 s7, s29, 0
	global_load_dwordx4 v[24:27], v2, s[6:7] offset:1024
	s_add_i32 s0, s24, -2
	s_max_i32 s0, s0, 0
	s_min_i32 s0, s0, s26
	s_add_i32 s0, s0, s23
	s_lshl_b32 s0, s0, 11
	s_add_u32 s6, s28, s0
	s_addc_u32 s7, s29, 0
	global_load_dwordx4 v[28:31], v2, s[6:7] offset:1024
	s_add_i32 s0, s24, -1
	s_max_i32 s0, s0, 0
	s_min_i32 s0, s0, s26
	s_add_i32 s0, s0, s23
	s_lshl_b32 s0, s0, 11
	s_add_u32 s6, s28, s0
	s_addc_u32 s7, s29, 0
	global_load_dwordx4 v[32:35], v2, s[6:7] offset:1024
	s_add_i32 s0, s24, 0
	s_max_i32 s0, s0, 0
	s_min_i32 s0, s0, s26
	s_add_i32 s0, s0, s23
	s_lshl_b32 s0, s0, 11
	s_add_u32 s6, s28, s0
	s_addc_u32 s7, s29, 0
	global_load_dwordx4 v[36:39], v2, s[6:7] offset:1024
	s_add_i32 s0, s24, 1
	s_max_i32 s0, s0, 0
	s_min_i32 s0, s0, s26
	s_add_i32 s0, s0, s23
	s_lshl_b32 s0, s0, 11
	s_add_u32 s6, s28, s0
	s_addc_u32 s7, s29, 0
	global_load_dwordx4 v[40:43], v2, s[6:7] offset:1024
	s_add_i32 s0, s24, 2
	s_max_i32 s0, s0, 0
	s_min_i32 s0, s0, s26
	s_add_i32 s0, s0, s23
	s_lshl_b32 s0, s0, 11
	s_add_u32 s6, s28, s0
	s_addc_u32 s7, s29, 0
	global_load_dwordx4 v[44:47], v2, s[6:7] offset:1024
	s_add_i32 s0, s24, 3
	s_max_i32 s0, s0, 0
	s_min_i32 s0, s0, s26
	s_add_i32 s0, s0, s23
	s_lshl_b32 s0, s0, 11
	s_add_u32 s6, s28, s0
	s_addc_u32 s7, s29, 0
	global_load_dwordx4 v[48:51], v2, s[6:7] offset:1024
	s_add_i32 s0, s24, 4
	s_max_i32 s0, s0, 0
	s_min_i32 s0, s0, s26
	s_add_i32 s0, s0, s23
	s_lshl_b32 s0, s0, 11
	s_add_u32 s6, s28, s0
	s_addc_u32 s7, s29, 0
	global_load_dwordx4 v[52:55], v2, s[6:7] offset:1024
	s_add_i32 s0, s24, 5
	s_max_i32 s0, s0, 0
	s_min_i32 s0, s0, s26
	s_add_i32 s0, s0, s23
	s_lshl_b32 s0, s0, 11
	s_add_u32 s6, s28, s0
	s_addc_u32 s7, s29, 0
	global_load_dwordx4 v[56:59], v2, s[6:7] offset:1024
	s_add_i32 s0, s24, 6
	s_max_i32 s0, s0, 0
	s_min_i32 s0, s0, s26
	s_add_i32 s0, s0, s23
	s_lshl_b32 s0, s0, 11
	s_add_u32 s6, s28, s0
	s_addc_u32 s7, s29, 0
	global_load_dwordx4 v[60:63], v2, s[6:7] offset:1024
	s_add_i32 s0, s24, 7
	s_max_i32 s0, s0, 0
	s_min_i32 s0, s0, s26
	s_add_i32 s0, s0, s23
	s_lshl_b32 s0, s0, 11
	s_add_u32 s6, s28, s0
	s_addc_u32 s7, s29, 0
	global_load_dwordx4 v[64:67], v2, s[6:7] offset:1024
	s_add_i32 s0, s24, 8
	s_max_i32 s0, s0, 0
	s_min_i32 s0, s0, s26
	s_add_i32 s0, s0, s23
	s_lshl_b32 s0, s0, 11
	s_add_u32 s6, s28, s0
	s_addc_u32 s7, s29, 0
	global_load_dwordx4 v[68:71], v2, s[6:7] offset:1024
	s_add_i32 s0, s24, 9
	s_max_i32 s0, s0, 0
	s_min_i32 s0, s0, s26
	s_add_i32 s0, s0, s23
	s_lshl_b32 s0, s0, 11
	s_add_u32 s6, s28, s0
	s_addc_u32 s7, s29, 0
	global_load_dwordx4 v[72:75], v2, s[6:7] offset:1024
	s_add_i32 s0, s24, 10
	s_max_i32 s0, s0, 0
	s_min_i32 s0, s0, s26
	s_add_i32 s0, s0, s23
	s_lshl_b32 s0, s0, 11
	s_add_u32 s6, s28, s0
	s_addc_u32 s7, s29, 0
	global_load_dwordx4 v[76:79], v2, s[6:7] offset:1024
	s_add_i32 s0, s24, -2
	s_max_i32 s0, s0, 0
	s_min_i32 s0, s0, s26
	s_add_i32 s0, s0, s23
	s_lshl_b32 s0, s0, 11
	s_add_u32 s6, s28, s0
	s_addc_u32 s7, s29, 0
	global_load_dwordx4 v[80:83], v2, s[6:7]
	s_add_i32 s0, s24, -1
	s_max_i32 s0, s0, 0
	s_min_i32 s0, s0, s26
	s_add_i32 s0, s0, s23
	s_lshl_b32 s0, s0, 11
	s_add_u32 s6, s28, s0
	s_addc_u32 s7, s29, 0
	global_load_dwordx4 v[84:87], v2, s[6:7]
	s_add_i32 s0, s24, 0
	s_max_i32 s0, s0, 0
	s_min_i32 s0, s0, s26
	s_add_i32 s0, s0, s23
	s_lshl_b32 s0, s0, 11
	s_add_u32 s6, s28, s0
	s_addc_u32 s7, s29, 0
	global_load_dwordx4 v[88:91], v2, s[6:7]
	s_add_i32 s0, s24, 1
	s_max_i32 s0, s0, 0
	s_min_i32 s0, s0, s26
	s_add_i32 s0, s0, s23
	s_lshl_b32 s0, s0, 11
	s_add_u32 s6, s28, s0
	s_addc_u32 s7, s29, 0
	global_load_dwordx4 v[92:95], v2, s[6:7]
	s_add_i32 s0, s24, 2
	s_max_i32 s0, s0, 0
	s_min_i32 s0, s0, s26
	s_add_i32 s0, s0, s23
	s_lshl_b32 s0, s0, 11
	s_add_u32 s6, s28, s0
	s_addc_u32 s7, s29, 0
	global_load_dwordx4 v[96:99], v2, s[6:7]
	s_add_i32 s0, s24, 3
	s_max_i32 s0, s0, 0
	s_min_i32 s0, s0, s26
	s_add_i32 s0, s0, s23
	s_lshl_b32 s0, s0, 11
	s_add_u32 s6, s28, s0
	s_addc_u32 s7, s29, 0
	global_load_dwordx4 v[100:103], v2, s[6:7]
	s_add_i32 s0, s24, 4
	s_max_i32 s0, s0, 0
	s_min_i32 s0, s0, s26
	s_add_i32 s0, s0, s23
	s_lshl_b32 s0, s0, 11
	s_add_u32 s6, s28, s0
	s_addc_u32 s7, s29, 0
	global_load_dwordx4 v[104:107], v2, s[6:7]
	s_add_i32 s0, s24, 4
	s_min_i32 s0, s0, s25
	s_add_i32 s1, s24, -4
	s_max_i32 s1, s1, 0
	s_sub_i32 s30, s0, s1
	s_add_i32 s0, s24, 8
	s_min_i32 s0, s0, s25
	s_add_i32 s1, s24, -8
	s_max_i32 s1, s1, 0
	s_sub_i32 s31, s0, s1
	v_mov_b32_e32 v172, s30
	v_mov_b32_e32 v173, s31
	v_cndmask_b32_e64 v172, v172, v173, s[34:35]
	v_cvt_f32_u32_e32 v172, v172
	v_rcp_f32_e32 v173, v172
	s_nop 0
	v_fma_f32 v174, -v172, v173, 1.0
	v_fmac_f32_e32 v173, v174, v173
	v_mov_b32_e32 v152, v173
	s_add_i32 s0, s24, 5
	s_min_i32 s0, s0, s25
	s_add_i32 s1, s24, -3
	s_max_i32 s1, s1, 0
	s_sub_i32 s30, s0, s1
	s_add_i32 s0, s24, 9
	s_min_i32 s0, s0, s25
	s_add_i32 s1, s24, -7
	s_max_i32 s1, s1, 0
	s_sub_i32 s31, s0, s1
	v_mov_b32_e32 v172, s30
	v_mov_b32_e32 v173, s31
	v_cndmask_b32_e64 v172, v172, v173, s[34:35]
	v_cvt_f32_u32_e32 v172, v172
	v_rcp_f32_e32 v173, v172
	s_nop 0
	v_fma_f32 v174, -v172, v173, 1.0
	v_fmac_f32_e32 v173, v174, v173
	v_mov_b32_e32 v154, v173
	s_add_i32 s0, s24, 6
	s_min_i32 s0, s0, s25
	s_add_i32 s1, s24, -2
	s_max_i32 s1, s1, 0
	s_sub_i32 s30, s0, s1
	s_add_i32 s0, s24, 10
	s_min_i32 s0, s0, s25
	s_add_i32 s1, s24, -6
	s_max_i32 s1, s1, 0
	s_sub_i32 s31, s0, s1
	v_mov_b32_e32 v172, s30
	v_mov_b32_e32 v173, s31
	v_cndmask_b32_e64 v172, v172, v173, s[34:35]
	v_cvt_f32_u32_e32 v172, v172
	v_rcp_f32_e32 v173, v172
	s_nop 0
	v_fma_f32 v174, -v172, v173, 1.0
	v_fmac_f32_e32 v173, v174, v173
	v_mov_b32_e32 v156, v173
	s_add_i32 s0, s24, 7
	s_min_i32 s0, s0, s25
	s_add_i32 s1, s24, -1
	s_max_i32 s1, s1, 0
	s_sub_i32 s30, s0, s1
	s_add_i32 s0, s24, 11
	s_min_i32 s0, s0, s25
	s_add_i32 s1, s24, -5
	s_max_i32 s1, s1, 0
	s_sub_i32 s31, s0, s1
	v_mov_b32_e32 v172, s30
	v_mov_b32_e32 v173, s31
	v_cndmask_b32_e64 v172, v172, v173, s[34:35]
	v_cvt_f32_u32_e32 v172, v172
	v_rcp_f32_e32 v173, v172
	s_nop 0
	v_fma_f32 v174, -v172, v173, 1.0
	v_fmac_f32_e32 v173, v174, v173
	v_mov_b32_e32 v158, v173
	v_mov_b32_e32 v108, 0
	v_mov_b32_e32 v109, 0
	v_mov_b32_e32 v110, 0
	v_mov_b32_e32 v111, 0
	v_mov_b32_e32 v112, 0
	v_mov_b32_e32 v113, 0
	v_mov_b32_e32 v114, 0
	v_mov_b32_e32 v115, 0
	v_mov_b32_e32 v116, 0
	v_mov_b32_e32 v117, 0
	v_mov_b32_e32 v118, 0
	v_mov_b32_e32 v119, 0
	v_mov_b32_e32 v120, 0
	v_mov_b32_e32 v121, 0
	v_mov_b32_e32 v122, 0
	v_mov_b32_e32 v123, 0
	v_mov_b32_e32 v124, 0
	v_mov_b32_e32 v125, 0
	v_mov_b32_e32 v126, 0
	v_mov_b32_e32 v127, 0
	v_mov_b32_e32 v128, 0
	v_mov_b32_e32 v129, 0
	v_mov_b32_e32 v130, 0
	v_mov_b32_e32 v131, 0
	v_mov_b32_e32 v132, 0
	v_mov_b32_e32 v133, 0
	v_mov_b32_e32 v134, 0
	v_mov_b32_e32 v135, 0
	v_mov_b32_e32 v136, 0
	v_mov_b32_e32 v137, 0
	v_mov_b32_e32 v138, 0
	v_mov_b32_e32 v139, 0
	s_waitcnt vmcnt(25)
	s_add_i32 s0, s24, -8
	s_cmp_lt_u32 s0, s25
	s_cselect_b32 s1, 1.0, 0
	v_lshlrev_b32_e32 v140, 16, v4
	v_and_b32_e32 v141, 0xffff0000, v4
	v_lshlrev_b32_e32 v142, 16, v5
	v_and_b32_e32 v143, 0xffff0000, v5
	v_lshlrev_b32_e32 v144, 16, v6
	v_and_b32_e32 v145, 0xffff0000, v6
	v_lshlrev_b32_e32 v146, 16, v7
	v_and_b32_e32 v147, 0xffff0000, v7
	v_mov_b32_e32 v148, s1
	v_mul_f32_e32 v150, s1, v3
	v_pk_fma_f32 v[108:109], v[150:151], v[140:141], v[108:109] op_sel_hi:[0,1,1]
	v_pk_fma_f32 v[110:111], v[150:151], v[142:143], v[110:111] op_sel_hi:[0,1,1]
	v_pk_fma_f32 v[112:113], v[150:151], v[144:145], v[112:113] op_sel_hi:[0,1,1]
	v_pk_fma_f32 v[114:115], v[150:151], v[146:147], v[114:115] op_sel_hi:[0,1,1]
	s_waitcnt vmcnt(24)
	s_add_i32 s0, s24, -7
	s_cmp_lt_u32 s0, s25
	s_cselect_b32 s1, 1.0, 0
	v_lshlrev_b32_e32 v140, 16, v8
	v_and_b32_e32 v141, 0xffff0000, v8
	v_lshlrev_b32_e32 v142, 16, v9
	v_and_b32_e32 v143, 0xffff0000, v9
	v_lshlrev_b32_e32 v144, 16, v10
	v_and_b32_e32 v145, 0xffff0000, v10
	v_lshlrev_b32_e32 v146, 16, v11
	v_and_b32_e32 v147, 0xffff0000, v11
	v_mov_b32_e32 v148, s1
	v_mul_f32_e32 v150, s1, v3
	v_pk_fma_f32 v[108:109], v[150:151], v[140:141], v[108:109] op_sel_hi:[0,1,1]
	v_pk_fma_f32 v[110:111], v[150:151], v[142:143], v[110:111] op_sel_hi:[0,1,1]
	v_pk_fma_f32 v[112:113], v[150:151], v[144:145], v[112:113] op_sel_hi:[0,1,1]
	v_pk_fma_f32 v[114:115], v[150:151], v[146:147], v[114:115] op_sel_hi:[0,1,1]
	v_pk_fma_f32 v[116:117], v[150:151], v[140:141], v[116:117] op_sel_hi:[0,1,1]
	v_pk_fma_f32 v[118:119], v[150:151], v[142:143], v[118:119] op_sel_hi:[0,1,1]
	v_pk_fma_f32 v[120:121], v[150:151], v[144:145], v[120:121] op_sel_hi:[0,1,1]
	v_pk_fma_f32 v[122:123], v[150:151], v[146:147], v[122:123] op_sel_hi:[0,1,1]
	s_waitcnt vmcnt(23)
	s_add_i32 s0, s24, -6
	s_cmp_lt_u32 s0, s25
	s_cselect_b32 s1, 1.0, 0
	v_lshlrev_b32_e32 v140, 16, v12
	v_and_b32_e32 v141, 0xffff0000, v12
	v_lshlrev_b32_e32 v142, 16, v13
	v_and_b32_e32 v143, 0xffff0000, v13
	v_lshlrev_b32_e32 v144, 16, v14
	v_and_b32_e32 v145, 0xffff0000, v14
	v_lshlrev_b32_e32 v146, 16, v15
	v_and_b32_e32 v147, 0xffff0000, v15
	v_mov_b32_e32 v148, s1
	v_mul_f32_e32 v150, s1, v3
	v_pk_fma_f32 v[108:109], v[150:151], v[140:141], v[108:109] op_sel_hi:[0,1,1]
	v_pk_fma_f32 v[110:111], v[150:151], v[142:143], v[110:111] op_sel_hi:[0,1,1]
	v_pk_fma_f32 v[112:113], v[150:151], v[144:145], v[112:113] op_sel_hi:[0,1,1]
	v_pk_fma_f32 v[114:115], v[150:151], v[146:147], v[114:115] op_sel_hi:[0,1,1]
	v_pk_fma_f32 v[116:117], v[150:151], v[140:141], v[116:117] op_sel_hi:[0,1,1]
	v_pk_fma_f32 v[118:119], v[150:151], v[142:143], v[118:119] op_sel_hi:[0,1,1]
	v_pk_fma_f32 v[120:121], v[150:151], v[144:145], v[120:121] op_sel_hi:[0,1,1]
	v_pk_fma_f32 v[122:123], v[150:151], v[146:147], v[122:123] op_sel_hi:[0,1,1]
	v_pk_fma_f32 v[124:125], v[150:151], v[140:141], v[124:125] op_sel_hi:[0,1,1]
	v_pk_fma_f32 v[126:127], v[150:151], v[142:143], v[126:127] op_sel_hi:[0,1,1]
	v_pk_fma_f32 v[128:129], v[150:151], v[144:145], v[128:129] op_sel_hi:[0,1,1]
	v_pk_fma_f32 v[130:131], v[150:151], v[146:147], v[130:131] op_sel_hi:[0,1,1]
	s_waitcnt vmcnt(22)
	s_add_i32 s0, s24, -5
	s_cmp_lt_u32 s0, s25
	s_cselect_b32 s1, 1.0, 0
	v_lshlrev_b32_e32 v140, 16, v16
	v_and_b32_e32 v141, 0xffff0000, v16
	v_lshlrev_b32_e32 v142, 16, v17
	v_and_b32_e32 v143, 0xffff0000, v17
	v_lshlrev_b32_e32 v144, 16, v18
	v_and_b32_e32 v145, 0xffff0000, v18
	v_lshlrev_b32_e32 v146, 16, v19
	v_and_b32_e32 v147, 0xffff0000, v19
	v_mov_b32_e32 v148, s1
	v_mul_f32_e32 v150, s1, v3
	v_pk_fma_f32 v[108:109], v[150:151], v[140:141], v[108:109] op_sel_hi:[0,1,1]
	v_pk_fma_f32 v[110:111], v[150:151], v[142:143], v[110:111] op_sel_hi:[0,1,1]
	v_pk_fma_f32 v[112:113], v[150:151], v[144:145], v[112:113] op_sel_hi:[0,1,1]
	v_pk_fma_f32 v[114:115], v[150:151], v[146:147], v[114:115] op_sel_hi:[0,1,1]
	v_pk_fma_f32 v[116:117], v[150:151], v[140:141], v[116:117] op_sel_hi:[0,1,1]
	v_pk_fma_f32 v[118:119], v[150:151], v[142:143], v[118:119] op_sel_hi:[0,1,1]
	v_pk_fma_f32 v[120:121], v[150:151], v[144:145], v[120:121] op_sel_hi:[0,1,1]
	v_pk_fma_f32 v[122:123], v[150:151], v[146:147], v[122:123] op_sel_hi:[0,1,1]
	v_pk_fma_f32 v[124:125], v[150:151], v[140:141], v[124:125] op_sel_hi:[0,1,1]
	v_pk_fma_f32 v[126:127], v[150:151], v[142:143], v[126:127] op_sel_hi:[0,1,1]
	v_pk_fma_f32 v[128:129], v[150:151], v[144:145], v[128:129] op_sel_hi:[0,1,1]
	v_pk_fma_f32 v[130:131], v[150:151], v[146:147], v[130:131] op_sel_hi:[0,1,1]
	v_pk_fma_f32 v[132:133], v[150:151], v[140:141], v[132:133] op_sel_hi:[0,1,1]
	v_pk_fma_f32 v[134:135], v[150:151], v[142:143], v[134:135] op_sel_hi:[0,1,1]
	v_pk_fma_f32 v[136:137], v[150:151], v[144:145], v[136:137] op_sel_hi:[0,1,1]
	v_pk_fma_f32 v[138:139], v[150:151], v[146:147], v[138:139] op_sel_hi:[0,1,1]
	s_waitcnt vmcnt(21)
	s_add_i32 s0, s24, -4
	s_cmp_lt_u32 s0, s25
	s_cselect_b32 s1, 1.0, 0
	v_lshlrev_b32_e32 v140, 16, v20
	v_and_b32_e32 v141, 0xffff0000, v20
	v_lshlrev_b32_e32 v142, 16, v21
	v_and_b32_e32 v143, 0xffff0000, v21
	v_lshlrev_b32_e32 v144, 16, v22
	v_and_b32_e32 v145, 0xffff0000, v22
	v_lshlrev_b32_e32 v146, 16, v23
	v_and_b32_e32 v147, 0xffff0000, v23
	v_mov_b32_e32 v148, s1
	v_mul_f32_e32 v150, s1, v3
	v_pk_fma_f32 v[108:109], v[148:149], v[140:141], v[108:109] op_sel_hi:[0,1,1]
	v_pk_fma_f32 v[110:111], v[148:149], v[142:143], v[110:111] op_sel_hi:[0,1,1]
	v_pk_fma_f32 v[112:113], v[148:149], v[144:145], v[112:113] op_sel_hi:[0,1,1]
	v_pk_fma_f32 v[114:115], v[148:149], v[146:147], v[114:115] op_sel_hi:[0,1,1]
	v_pk_fma_f32 v[116:117], v[150:151], v[140:141], v[116:117] op_sel_hi:[0,1,1]
	v_pk_fma_f32 v[118:119], v[150:151], v[142:143], v[118:119] op_sel_hi:[0,1,1]
	v_pk_fma_f32 v[120:121], v[150:151], v[144:145], v[120:121] op_sel_hi:[0,1,1]
	v_pk_fma_f32 v[122:123], v[150:151], v[146:147], v[122:123] op_sel_hi:[0,1,1]
	v_pk_fma_f32 v[124:125], v[150:151], v[140:141], v[124:125] op_sel_hi:[0,1,1]
	v_pk_fma_f32 v[126:127], v[150:151], v[142:143], v[126:127] op_sel_hi:[0,1,1]
	v_pk_fma_f32 v[128:129], v[150:151], v[144:145], v[128:129] op_sel_hi:[0,1,1]
	v_pk_fma_f32 v[130:131], v[150:151], v[146:147], v[130:131] op_sel_hi:[0,1,1]
	v_pk_fma_f32 v[132:133], v[150:151], v[140:141], v[132:133] op_sel_hi:[0,1,1]
	v_pk_fma_f32 v[134:135], v[150:151], v[142:143], v[134:135] op_sel_hi:[0,1,1]
	v_pk_fma_f32 v[136:137], v[150:151], v[144:145], v[136:137] op_sel_hi:[0,1,1]
	v_pk_fma_f32 v[138:139], v[150:151], v[146:147], v[138:139] op_sel_hi:[0,1,1]
	s_waitcnt vmcnt(20)
	s_add_i32 s0, s24, -3
	s_cmp_lt_u32 s0, s25
	s_cselect_b32 s1, 1.0, 0
	v_lshlrev_b32_e32 v140, 16, v24
	v_and_b32_e32 v141, 0xffff0000, v24
	v_lshlrev_b32_e32 v142, 16, v25
	v_and_b32_e32 v143, 0xffff0000, v25
	v_lshlrev_b32_e32 v144, 16, v26
	v_and_b32_e32 v145, 0xffff0000, v26
	v_lshlrev_b32_e32 v146, 16, v27
	v_and_b32_e32 v147, 0xffff0000, v27
	v_mov_b32_e32 v148, s1
	v_mul_f32_e32 v150, s1, v3
	v_pk_fma_f32 v[108:109], v[148:149], v[140:141], v[108:109] op_sel_hi:[0,1,1]
	v_pk_fma_f32 v[110:111], v[148:149], v[142:143], v[110:111] op_sel_hi:[0,1,1]
	v_pk_fma_f32 v[112:113], v[148:149], v[144:145], v[112:113] op_sel_hi:[0,1,1]
	v_pk_fma_f32 v[114:115], v[148:149], v[146:147], v[114:115] op_sel_hi:[0,1,1]
	v_pk_fma_f32 v[116:117], v[148:149], v[140:141], v[116:117] op_sel_hi:[0,1,1]
	v_pk_fma_f32 v[118:119], v[148:149], v[142:143], v[118:119] op_sel_hi:[0,1,1]
	v_pk_fma_f32 v[120:121], v[148:149], v[144:145], v[120:121] op_sel_hi:[0,1,1]
	v_pk_fma_f32 v[122:123], v[148:149], v[146:147], v[122:123] op_sel_hi:[0,1,1]
	v_pk_fma_f32 v[124:125], v[150:151], v[140:141], v[124:125] op_sel_hi:[0,1,1]
	v_pk_fma_f32 v[126:127], v[150:151], v[142:143], v[126:127] op_sel_hi:[0,1,1]
	v_pk_fma_f32 v[128:129], v[150:151], v[144:145], v[128:129] op_sel_hi:[0,1,1]
	v_pk_fma_f32 v[130:131], v[150:151], v[146:147], v[130:131] op_sel_hi:[0,1,1]
	v_pk_fma_f32 v[132:133], v[150:151], v[140:141], v[132:133] op_sel_hi:[0,1,1]
	v_pk_fma_f32 v[134:135], v[150:151], v[142:143], v[134:135] op_sel_hi:[0,1,1]
	v_pk_fma_f32 v[136:137], v[150:151], v[144:145], v[136:137] op_sel_hi:[0,1,1]
	v_pk_fma_f32 v[138:139], v[150:151], v[146:147], v[138:139] op_sel_hi:[0,1,1]
	s_waitcnt vmcnt(19)
	s_add_i32 s0, s24, -2
	s_cmp_lt_u32 s0, s25
	s_cselect_b32 s1, 1.0, 0
	v_lshlrev_b32_e32 v140, 16, v28
	v_and_b32_e32 v141, 0xffff0000, v28
	v_lshlrev_b32_e32 v142, 16, v29
	v_and_b32_e32 v143, 0xffff0000, v29
	v_lshlrev_b32_e32 v144, 16, v30
	v_and_b32_e32 v145, 0xffff0000, v30
	v_lshlrev_b32_e32 v146, 16, v31
	v_and_b32_e32 v147, 0xffff0000, v31
	v_mov_b32_e32 v148, s1
	v_mul_f32_e32 v150, s1, v3
	v_pk_fma_f32 v[108:109], v[148:149], v[140:141], v[108:109] op_sel_hi:[0,1,1]
	v_pk_fma_f32 v[110:111], v[148:149], v[142:143], v[110:111] op_sel_hi:[0,1,1]
	v_pk_fma_f32 v[112:113], v[148:149], v[144:145], v[112:113] op_sel_hi:[0,1,1]
	v_pk_fma_f32 v[114:115], v[148:149], v[146:147], v[114:115] op_sel_hi:[0,1,1]
	v_pk_fma_f32 v[116:117], v[148:149], v[140:141], v[116:117] op_sel_hi:[0,1,1]
	v_pk_fma_f32 v[118:119], v[148:149], v[142:143], v[118:119] op_sel_hi:[0,1,1]
	v_pk_fma_f32 v[120:121], v[148:149], v[144:145], v[120:121] op_sel_hi:[0,1,1]
	v_pk_fma_f32 v[122:123], v[148:149], v[146:147], v[122:123] op_sel_hi:[0,1,1]
	v_pk_fma_f32 v[124:125], v[148:149], v[140:141], v[124:125] op_sel_hi:[0,1,1]
	v_pk_fma_f32 v[126:127], v[148:149], v[142:143], v[126:127] op_sel_hi:[0,1,1]
	v_pk_fma_f32 v[128:129], v[148:149], v[144:145], v[128:129] op_sel_hi:[0,1,1]
	v_pk_fma_f32 v[130:131], v[148:149], v[146:147], v[130:131] op_sel_hi:[0,1,1]
	v_pk_fma_f32 v[132:133], v[150:151], v[140:141], v[132:133] op_sel_hi:[0,1,1]
	v_pk_fma_f32 v[134:135], v[150:151], v[142:143], v[134:135] op_sel_hi:[0,1,1]
	v_pk_fma_f32 v[136:137], v[150:151], v[144:145], v[136:137] op_sel_hi:[0,1,1]
	v_pk_fma_f32 v[138:139], v[150:151], v[146:147], v[138:139] op_sel_hi:[0,1,1]
	s_waitcnt vmcnt(18)
	s_add_i32 s0, s24, -1
	s_cmp_lt_u32 s0, s25
	s_cselect_b32 s1, 1.0, 0
	v_lshlrev_b32_e32 v140, 16, v32
	v_and_b32_e32 v141, 0xffff0000, v32
	v_lshlrev_b32_e32 v142, 16, v33
	v_and_b32_e32 v143, 0xffff0000, v33
	v_lshlrev_b32_e32 v144, 16, v34
	v_and_b32_e32 v145, 0xffff0000, v34
	v_lshlrev_b32_e32 v146, 16, v35
	v_and_b32_e32 v147, 0xffff0000, v35
	v_mov_b32_e32 v148, s1
	v_mul_f32_e32 v150, s1, v3
	v_pk_fma_f32 v[108:109], v[148:149], v[140:141], v[108:109] op_sel_hi:[0,1,1]
	v_pk_fma_f32 v[110:111], v[148:149], v[142:143], v[110:111] op_sel_hi:[0,1,1]
	v_pk_fma_f32 v[112:113], v[148:149], v[144:145], v[112:113] op_sel_hi:[0,1,1]
	v_pk_fma_f32 v[114:115], v[148:149], v[146:147], v[114:115] op_sel_hi:[0,1,1]
	v_pk_fma_f32 v[116:117], v[148:149], v[140:141], v[116:117] op_sel_hi:[0,1,1]
	v_pk_fma_f32 v[118:119], v[148:149], v[142:143], v[118:119] op_sel_hi:[0,1,1]
	v_pk_fma_f32 v[120:121], v[148:149], v[144:145], v[120:121] op_sel_hi:[0,1,1]
	v_pk_fma_f32 v[122:123], v[148:149], v[146:147], v[122:123] op_sel_hi:[0,1,1]
	v_pk_fma_f32 v[124:125], v[148:149], v[140:141], v[124:125] op_sel_hi:[0,1,1]
	v_pk_fma_f32 v[126:127], v[148:149], v[142:143], v[126:127] op_sel_hi:[0,1,1]
	v_pk_fma_f32 v[128:129], v[148:149], v[144:145], v[128:129] op_sel_hi:[0,1,1]
	v_pk_fma_f32 v[130:131], v[148:149], v[146:147], v[130:131] op_sel_hi:[0,1,1]
	v_pk_fma_f32 v[132:133], v[148:149], v[140:141], v[132:133] op_sel_hi:[0,1,1]
	v_pk_fma_f32 v[134:135], v[148:149], v[142:143], v[134:135] op_sel_hi:[0,1,1]
	v_pk_fma_f32 v[136:137], v[148:149], v[144:145], v[136:137] op_sel_hi:[0,1,1]
	v_pk_fma_f32 v[138:139], v[148:149], v[146:147], v[138:139] op_sel_hi:[0,1,1]
	s_waitcnt vmcnt(17)
	s_add_i32 s0, s24, 0
	s_cmp_lt_u32 s0, s25
	s_cselect_b32 s1, 1.0, 0
	v_lshlrev_b32_e32 v140, 16, v36
	v_and_b32_e32 v141, 0xffff0000, v36
	v_lshlrev_b32_e32 v142, 16, v37
	v_and_b32_e32 v143, 0xffff0000, v37
	v_lshlrev_b32_e32 v144, 16, v38
	v_and_b32_e32 v145, 0xffff0000, v38
	v_lshlrev_b32_e32 v146, 16, v39
	v_and_b32_e32 v147, 0xffff0000, v39
	v_mov_b32_e32 v148, s1
	v_mul_f32_e32 v150, s1, v3
	v_pk_fma_f32 v[108:109], v[148:149], v[140:141], v[108:109] op_sel_hi:[0,1,1]
	v_pk_fma_f32 v[110:111], v[148:149], v[142:143], v[110:111] op_sel_hi:[0,1,1]
	v_pk_fma_f32 v[112:113], v[148:149], v[144:145], v[112:113] op_sel_hi:[0,1,1]
	v_pk_fma_f32 v[114:115], v[148:149], v[146:147], v[114:115] op_sel_hi:[0,1,1]
	v_pk_fma_f32 v[116:117], v[148:149], v[140:141], v[116:117] op_sel_hi:[0,1,1]
	v_pk_fma_f32 v[118:119], v[148:149], v[142:143], v[118:119] op_sel_hi:[0,1,1]
	v_pk_fma_f32 v[120:121], v[148:149], v[144:145], v[120:121] op_sel_hi:[0,1,1]
	v_pk_fma_f32 v[122:123], v[148:149], v[146:147], v[122:123] op_sel_hi:[0,1,1]
	v_pk_fma_f32 v[124:125], v[148:149], v[140:141], v[124:125] op_sel_hi:[0,1,1]
	v_pk_fma_f32 v[126:127], v[148:149], v[142:143], v[126:127] op_sel_hi:[0,1,1]
	v_pk_fma_f32 v[128:129], v[148:149], v[144:145], v[128:129] op_sel_hi:[0,1,1]
	v_pk_fma_f32 v[130:131], v[148:149], v[146:147], v[130:131] op_sel_hi:[0,1,1]
	v_pk_fma_f32 v[132:133], v[148:149], v[140:141], v[132:133] op_sel_hi:[0,1,1]
	v_pk_fma_f32 v[134:135], v[148:149], v[142:143], v[134:135] op_sel_hi:[0,1,1]
	v_pk_fma_f32 v[136:137], v[148:149], v[144:145], v[136:137] op_sel_hi:[0,1,1]
	v_pk_fma_f32 v[138:139], v[148:149], v[146:147], v[138:139] op_sel_hi:[0,1,1]
	s_waitcnt vmcnt(16)
	s_add_i32 s0, s24, 1
	s_cmp_lt_u32 s0, s25
	s_cselect_b32 s1, 1.0, 0
	v_lshlrev_b32_e32 v140, 16, v40
	v_and_b32_e32 v141, 0xffff0000, v40
	v_lshlrev_b32_e32 v142, 16, v41
	v_and_b32_e32 v143, 0xffff0000, v41
	v_lshlrev_b32_e32 v144, 16, v42
	v_and_b32_e32 v145, 0xffff0000, v42
	v_lshlrev_b32_e32 v146, 16, v43
	v_and_b32_e32 v147, 0xffff0000, v43
	v_mov_b32_e32 v148, s1
	v_mul_f32_e32 v150, s1, v3
	v_pk_fma_f32 v[108:109], v[148:149], v[140:141], v[108:109] op_sel_hi:[0,1,1]
	v_pk_fma_f32 v[110:111], v[148:149], v[142:143], v[110:111] op_sel_hi:[0,1,1]
	v_pk_fma_f32 v[112:113], v[148:149], v[144:145], v[112:113] op_sel_hi:[0,1,1]
	v_pk_fma_f32 v[114:115], v[148:149], v[146:147], v[114:115] op_sel_hi:[0,1,1]
	v_pk_fma_f32 v[116:117], v[148:149], v[140:141], v[116:117] op_sel_hi:[0,1,1]
	v_pk_fma_f32 v[118:119], v[148:149], v[142:143], v[118:119] op_sel_hi:[0,1,1]
	v_pk_fma_f32 v[120:121], v[148:149], v[144:145], v[120:121] op_sel_hi:[0,1,1]
	v_pk_fma_f32 v[122:123], v[148:149], v[146:147], v[122:123] op_sel_hi:[0,1,1]
	v_pk_fma_f32 v[124:125], v[148:149], v[140:141], v[124:125] op_sel_hi:[0,1,1]
	v_pk_fma_f32 v[126:127], v[148:149], v[142:143], v[126:127] op_sel_hi:[0,1,1]
	v_pk_fma_f32 v[128:129], v[148:149], v[144:145], v[128:129] op_sel_hi:[0,1,1]
	v_pk_fma_f32 v[130:131], v[148:149], v[146:147], v[130:131] op_sel_hi:[0,1,1]
	v_pk_fma_f32 v[132:133], v[148:149], v[140:141], v[132:133] op_sel_hi:[0,1,1]
	v_pk_fma_f32 v[134:135], v[148:149], v[142:143], v[134:135] op_sel_hi:[0,1,1]
	v_pk_fma_f32 v[136:137], v[148:149], v[144:145], v[136:137] op_sel_hi:[0,1,1]
	v_pk_fma_f32 v[138:139], v[148:149], v[146:147], v[138:139] op_sel_hi:[0,1,1]
	s_waitcnt vmcnt(15)
	s_add_i32 s0, s24, 2
	s_cmp_lt_u32 s0, s25
	s_cselect_b32 s1, 1.0, 0
	v_lshlrev_b32_e32 v140, 16, v44
	v_and_b32_e32 v141, 0xffff0000, v44
	v_lshlrev_b32_e32 v142, 16, v45
	v_and_b32_e32 v143, 0xffff0000, v45
	v_lshlrev_b32_e32 v144, 16, v46
	v_and_b32_e32 v145, 0xffff0000, v46
	v_lshlrev_b32_e32 v146, 16, v47
	v_and_b32_e32 v147, 0xffff0000, v47
	v_mov_b32_e32 v148, s1
	v_mul_f32_e32 v150, s1, v3
	v_pk_fma_f32 v[108:109], v[148:149], v[140:141], v[108:109] op_sel_hi:[0,1,1]
	v_pk_fma_f32 v[110:111], v[148:149], v[142:143], v[110:111] op_sel_hi:[0,1,1]
	v_pk_fma_f32 v[112:113], v[148:149], v[144:145], v[112:113] op_sel_hi:[0,1,1]
	v_pk_fma_f32 v[114:115], v[148:149], v[146:147], v[114:115] op_sel_hi:[0,1,1]
	v_pk_fma_f32 v[116:117], v[148:149], v[140:141], v[116:117] op_sel_hi:[0,1,1]
	v_pk_fma_f32 v[118:119], v[148:149], v[142:143], v[118:119] op_sel_hi:[0,1,1]
	v_pk_fma_f32 v[120:121], v[148:149], v[144:145], v[120:121] op_sel_hi:[0,1,1]
	v_pk_fma_f32 v[122:123], v[148:149], v[146:147], v[122:123] op_sel_hi:[0,1,1]
	v_pk_fma_f32 v[124:125], v[148:149], v[140:141], v[124:125] op_sel_hi:[0,1,1]
	v_pk_fma_f32 v[126:127], v[148:149], v[142:143], v[126:127] op_sel_hi:[0,1,1]
	v_pk_fma_f32 v[128:129], v[148:149], v[144:145], v[128:129] op_sel_hi:[0,1,1]
	v_pk_fma_f32 v[130:131], v[148:149], v[146:147], v[130:131] op_sel_hi:[0,1,1]
	v_pk_fma_f32 v[132:133], v[148:149], v[140:141], v[132:133] op_sel_hi:[0,1,1]
	v_pk_fma_f32 v[134:135], v[148:149], v[142:143], v[134:135] op_sel_hi:[0,1,1]
	v_pk_fma_f32 v[136:137], v[148:149], v[144:145], v[136:137] op_sel_hi:[0,1,1]
	v_pk_fma_f32 v[138:139], v[148:149], v[146:147], v[138:139] op_sel_hi:[0,1,1]
	s_waitcnt vmcnt(14)
	s_add_i32 s0, s24, 3
	s_cmp_lt_u32 s0, s25
	s_cselect_b32 s1, 1.0, 0
	v_lshlrev_b32_e32 v140, 16, v48
	v_and_b32_e32 v141, 0xffff0000, v48
	v_lshlrev_b32_e32 v142, 16, v49
	v_and_b32_e32 v143, 0xffff0000, v49
	v_lshlrev_b32_e32 v144, 16, v50
	v_and_b32_e32 v145, 0xffff0000, v50
	v_lshlrev_b32_e32 v146, 16, v51
	v_and_b32_e32 v147, 0xffff0000, v51
	v_mov_b32_e32 v148, s1
	v_mul_f32_e32 v150, s1, v3
	v_pk_fma_f32 v[108:109], v[148:149], v[140:141], v[108:109] op_sel_hi:[0,1,1]
	v_pk_fma_f32 v[110:111], v[148:149], v[142:143], v[110:111] op_sel_hi:[0,1,1]
	v_pk_fma_f32 v[112:113], v[148:149], v[144:145], v[112:113] op_sel_hi:[0,1,1]
	v_pk_fma_f32 v[114:115], v[148:149], v[146:147], v[114:115] op_sel_hi:[0,1,1]
	v_pk_fma_f32 v[116:117], v[148:149], v[140:141], v[116:117] op_sel_hi:[0,1,1]
	v_pk_fma_f32 v[118:119], v[148:149], v[142:143], v[118:119] op_sel_hi:[0,1,1]
	v_pk_fma_f32 v[120:121], v[148:149], v[144:145], v[120:121] op_sel_hi:[0,1,1]
	v_pk_fma_f32 v[122:123], v[148:149], v[146:147], v[122:123] op_sel_hi:[0,1,1]
	v_pk_fma_f32 v[124:125], v[148:149], v[140:141], v[124:125] op_sel_hi:[0,1,1]
	v_pk_fma_f32 v[126:127], v[148:149], v[142:143], v[126:127] op_sel_hi:[0,1,1]
	v_pk_fma_f32 v[128:129], v[148:149], v[144:145], v[128:129] op_sel_hi:[0,1,1]
	v_pk_fma_f32 v[130:131], v[148:149], v[146:147], v[130:131] op_sel_hi:[0,1,1]
	v_pk_fma_f32 v[132:133], v[148:149], v[140:141], v[132:133] op_sel_hi:[0,1,1]
	v_pk_fma_f32 v[134:135], v[148:149], v[142:143], v[134:135] op_sel_hi:[0,1,1]
	v_pk_fma_f32 v[136:137], v[148:149], v[144:145], v[136:137] op_sel_hi:[0,1,1]
	v_pk_fma_f32 v[138:139], v[148:149], v[146:147], v[138:139] op_sel_hi:[0,1,1]
	s_waitcnt vmcnt(13)
	s_add_i32 s0, s24, 4
	s_cmp_lt_u32 s0, s25
	s_cselect_b32 s1, 1.0, 0
	v_lshlrev_b32_e32 v140, 16, v52
	v_and_b32_e32 v141, 0xffff0000, v52
	v_lshlrev_b32_e32 v142, 16, v53
	v_and_b32_e32 v143, 0xffff0000, v53
	v_lshlrev_b32_e32 v144, 16, v54
	v_and_b32_e32 v145, 0xffff0000, v54
	v_lshlrev_b32_e32 v146, 16, v55
	v_and_b32_e32 v147, 0xffff0000, v55
	v_mov_b32_e32 v148, s1
	v_mul_f32_e32 v150, s1, v3
	v_pk_fma_f32 v[108:109], v[150:151], v[140:141], v[108:109] op_sel_hi:[0,1,1]
	v_pk_fma_f32 v[110:111], v[150:151], v[142:143], v[110:111] op_sel_hi:[0,1,1]
	v_pk_fma_f32 v[112:113], v[150:151], v[144:145], v[112:113] op_sel_hi:[0,1,1]
	v_pk_fma_f32 v[114:115], v[150:151], v[146:147], v[114:115] op_sel_hi:[0,1,1]
	v_pk_fma_f32 v[116:117], v[148:149], v[140:141], v[116:117] op_sel_hi:[0,1,1]
	v_pk_fma_f32 v[118:119], v[148:149], v[142:143], v[118:119] op_sel_hi:[0,1,1]
	v_pk_fma_f32 v[120:121], v[148:149], v[144:145], v[120:121] op_sel_hi:[0,1,1]
	v_pk_fma_f32 v[122:123], v[148:149], v[146:147], v[122:123] op_sel_hi:[0,1,1]
	v_pk_fma_f32 v[124:125], v[148:149], v[140:141], v[124:125] op_sel_hi:[0,1,1]
	v_pk_fma_f32 v[126:127], v[148:149], v[142:143], v[126:127] op_sel_hi:[0,1,1]
	v_pk_fma_f32 v[128:129], v[148:149], v[144:145], v[128:129] op_sel_hi:[0,1,1]
	v_pk_fma_f32 v[130:131], v[148:149], v[146:147], v[130:131] op_sel_hi:[0,1,1]
	v_pk_fma_f32 v[132:133], v[148:149], v[140:141], v[132:133] op_sel_hi:[0,1,1]
	v_pk_fma_f32 v[134:135], v[148:149], v[142:143], v[134:135] op_sel_hi:[0,1,1]
	v_pk_fma_f32 v[136:137], v[148:149], v[144:145], v[136:137] op_sel_hi:[0,1,1]
	v_pk_fma_f32 v[138:139], v[148:149], v[146:147], v[138:139] op_sel_hi:[0,1,1]
	s_waitcnt vmcnt(12)
	s_add_i32 s0, s24, 5
	s_cmp_lt_u32 s0, s25
	s_cselect_b32 s1, 1.0, 0
	v_lshlrev_b32_e32 v140, 16, v56
	v_and_b32_e32 v141, 0xffff0000, v56
	v_lshlrev_b32_e32 v142, 16, v57
	v_and_b32_e32 v143, 0xffff0000, v57
	v_lshlrev_b32_e32 v144, 16, v58
	v_and_b32_e32 v145, 0xffff0000, v58
	v_lshlrev_b32_e32 v146, 16, v59
	v_and_b32_e32 v147, 0xffff0000, v59
	v_mov_b32_e32 v148, s1
	v_mul_f32_e32 v150, s1, v3
	v_pk_fma_f32 v[108:109], v[150:151], v[140:141], v[108:109] op_sel_hi:[0,1,1]
	v_pk_fma_f32 v[110:111], v[150:151], v[142:143], v[110:111] op_sel_hi:[0,1,1]
	v_pk_fma_f32 v[112:113], v[150:151], v[144:145], v[112:113] op_sel_hi:[0,1,1]
	v_pk_fma_f32 v[114:115], v[150:151], v[146:147], v[114:115] op_sel_hi:[0,1,1]
	v_pk_fma_f32 v[116:117], v[150:151], v[140:141], v[116:117] op_sel_hi:[0,1,1]
	v_pk_fma_f32 v[118:119], v[150:151], v[142:143], v[118:119] op_sel_hi:[0,1,1]
	v_pk_fma_f32 v[120:121], v[150:151], v[144:145], v[120:121] op_sel_hi:[0,1,1]
	v_pk_fma_f32 v[122:123], v[150:151], v[146:147], v[122:123] op_sel_hi:[0,1,1]
	v_pk_fma_f32 v[124:125], v[148:149], v[140:141], v[124:125] op_sel_hi:[0,1,1]
	v_pk_fma_f32 v[126:127], v[148:149], v[142:143], v[126:127] op_sel_hi:[0,1,1]
	v_pk_fma_f32 v[128:129], v[148:149], v[144:145], v[128:129] op_sel_hi:[0,1,1]
	v_pk_fma_f32 v[130:131], v[148:149], v[146:147], v[130:131] op_sel_hi:[0,1,1]
	v_pk_fma_f32 v[132:133], v[148:149], v[140:141], v[132:133] op_sel_hi:[0,1,1]
	v_pk_fma_f32 v[134:135], v[148:149], v[142:143], v[134:135] op_sel_hi:[0,1,1]
	v_pk_fma_f32 v[136:137], v[148:149], v[144:145], v[136:137] op_sel_hi:[0,1,1]
	v_pk_fma_f32 v[138:139], v[148:149], v[146:147], v[138:139] op_sel_hi:[0,1,1]
	s_waitcnt vmcnt(11)
	s_add_i32 s0, s24, 6
	s_cmp_lt_u32 s0, s25
	s_cselect_b32 s1, 1.0, 0
	v_lshlrev_b32_e32 v140, 16, v60
	v_and_b32_e32 v141, 0xffff0000, v60
	v_lshlrev_b32_e32 v142, 16, v61
	v_and_b32_e32 v143, 0xffff0000, v61
	v_lshlrev_b32_e32 v144, 16, v62
	v_and_b32_e32 v145, 0xffff0000, v62
	v_lshlrev_b32_e32 v146, 16, v63
	v_and_b32_e32 v147, 0xffff0000, v63
	v_mov_b32_e32 v148, s1
	v_mul_f32_e32 v150, s1, v3
	v_pk_fma_f32 v[108:109], v[150:151], v[140:141], v[108:109] op_sel_hi:[0,1,1]
	v_pk_fma_f32 v[110:111], v[150:151], v[142:143], v[110:111] op_sel_hi:[0,1,1]
	v_pk_fma_f32 v[112:113], v[150:151], v[144:145], v[112:113] op_sel_hi:[0,1,1]
	v_pk_fma_f32 v[114:115], v[150:151], v[146:147], v[114:115] op_sel_hi:[0,1,1]
	v_pk_fma_f32 v[116:117], v[150:151], v[140:141], v[116:117] op_sel_hi:[0,1,1]
	v_pk_fma_f32 v[118:119], v[150:151], v[142:143], v[118:119] op_sel_hi:[0,1,1]
	v_pk_fma_f32 v[120:121], v[150:151], v[144:145], v[120:121] op_sel_hi:[0,1,1]
	v_pk_fma_f32 v[122:123], v[150:151], v[146:147], v[122:123] op_sel_hi:[0,1,1]
	v_pk_fma_f32 v[124:125], v[150:151], v[140:141], v[124:125] op_sel_hi:[0,1,1]
	v_pk_fma_f32 v[126:127], v[150:151], v[142:143], v[126:127] op_sel_hi:[0,1,1]
	v_pk_fma_f32 v[128:129], v[150:151], v[144:145], v[128:129] op_sel_hi:[0,1,1]
	v_pk_fma_f32 v[130:131], v[150:151], v[146:147], v[130:131] op_sel_hi:[0,1,1]
	v_pk_fma_f32 v[132:133], v[148:149], v[140:141], v[132:133] op_sel_hi:[0,1,1]
	v_pk_fma_f32 v[134:135], v[148:149], v[142:143], v[134:135] op_sel_hi:[0,1,1]
	v_pk_fma_f32 v[136:137], v[148:149], v[144:145], v[136:137] op_sel_hi:[0,1,1]
	v_pk_fma_f32 v[138:139], v[148:149], v[146:147], v[138:139] op_sel_hi:[0,1,1]
	s_waitcnt vmcnt(10)
	s_add_i32 s0, s24, 7
	s_cmp_lt_u32 s0, s25
	s_cselect_b32 s1, 1.0, 0
	v_lshlrev_b32_e32 v140, 16, v64
	v_and_b32_e32 v141, 0xffff0000, v64
	v_lshlrev_b32_e32 v142, 16, v65
	v_and_b32_e32 v143, 0xffff0000, v65
	v_lshlrev_b32_e32 v144, 16, v66
	v_and_b32_e32 v145, 0xffff0000, v66
	v_lshlrev_b32_e32 v146, 16, v67
	v_and_b32_e32 v147, 0xffff0000, v67
	v_mov_b32_e32 v148, s1
	v_mul_f32_e32 v150, s1, v3
	v_pk_fma_f32 v[108:109], v[150:151], v[140:141], v[108:109] op_sel_hi:[0,1,1]
	v_pk_fma_f32 v[110:111], v[150:151], v[142:143], v[110:111] op_sel_hi:[0,1,1]
	v_pk_fma_f32 v[112:113], v[150:151], v[144:145], v[112:113] op_sel_hi:[0,1,1]
	v_pk_fma_f32 v[114:115], v[150:151], v[146:147], v[114:115] op_sel_hi:[0,1,1]
	v_pk_fma_f32 v[116:117], v[150:151], v[140:141], v[116:117] op_sel_hi:[0,1,1]
	v_pk_fma_f32 v[118:119], v[150:151], v[142:143], v[118:119] op_sel_hi:[0,1,1]
	v_pk_fma_f32 v[120:121], v[150:151], v[144:145], v[120:121] op_sel_hi:[0,1,1]
	v_pk_fma_f32 v[122:123], v[150:151], v[146:147], v[122:123] op_sel_hi:[0,1,1]
	v_pk_fma_f32 v[124:125], v[150:151], v[140:141], v[124:125] op_sel_hi:[0,1,1]
	v_pk_fma_f32 v[126:127], v[150:151], v[142:143], v[126:127] op_sel_hi:[0,1,1]
	v_pk_fma_f32 v[128:129], v[150:151], v[144:145], v[128:129] op_sel_hi:[0,1,1]
	v_pk_fma_f32 v[130:131], v[150:151], v[146:147], v[130:131] op_sel_hi:[0,1,1]
	v_pk_fma_f32 v[132:133], v[150:151], v[140:141], v[132:133] op_sel_hi:[0,1,1]
	v_pk_fma_f32 v[134:135], v[150:151], v[142:143], v[134:135] op_sel_hi:[0,1,1]
	v_pk_fma_f32 v[136:137], v[150:151], v[144:145], v[136:137] op_sel_hi:[0,1,1]
	v_pk_fma_f32 v[138:139], v[150:151], v[146:147], v[138:139] op_sel_hi:[0,1,1]
	s_waitcnt vmcnt(9)
	s_add_i32 s0, s24, 8
	s_cmp_lt_u32 s0, s25
	s_cselect_b32 s1, 1.0, 0
	v_lshlrev_b32_e32 v140, 16, v68
	v_and_b32_e32 v141, 0xffff0000, v68
	v_lshlrev_b32_e32 v142, 16, v69
	v_and_b32_e32 v143, 0xffff0000, v69
	v_lshlrev_b32_e32 v144, 16, v70
	v_and_b32_e32 v145, 0xffff0000, v70
	v_lshlrev_b32_e32 v146, 16, v71
	v_and_b32_e32 v147, 0xffff0000, v71
	v_mov_b32_e32 v148, s1
	v_mul_f32_e32 v150, s1, v3
	v_pk_fma_f32 v[116:117], v[150:151], v[140:141], v[116:117] op_sel_hi:[0,1,1]
	v_pk_fma_f32 v[118:119], v[150:151], v[142:143], v[118:119] op_sel_hi:[0,1,1]
	v_pk_fma_f32 v[120:121], v[150:151], v[144:145], v[120:121] op_sel_hi:[0,1,1]
	v_pk_fma_f32 v[122:123], v[150:151], v[146:147], v[122:123] op_sel_hi:[0,1,1]
	v_pk_fma_f32 v[124:125], v[150:151], v[140:141], v[124:125] op_sel_hi:[0,1,1]
	v_pk_fma_f32 v[126:127], v[150:151], v[142:143], v[126:127] op_sel_hi:[0,1,1]
	v_pk_fma_f32 v[128:129], v[150:151], v[144:145], v[128:129] op_sel_hi:[0,1,1]
	v_pk_fma_f32 v[130:131], v[150:151], v[146:147], v[130:131] op_sel_hi:[0,1,1]
	v_pk_fma_f32 v[132:133], v[150:151], v[140:141], v[132:133] op_sel_hi:[0,1,1]
	v_pk_fma_f32 v[134:135], v[150:151], v[142:143], v[134:135] op_sel_hi:[0,1,1]
	v_pk_fma_f32 v[136:137], v[150:151], v[144:145], v[136:137] op_sel_hi:[0,1,1]
	v_pk_fma_f32 v[138:139], v[150:151], v[146:147], v[138:139] op_sel_hi:[0,1,1]
	s_waitcnt vmcnt(8)
	s_add_i32 s0, s24, 9
	s_cmp_lt_u32 s0, s25
	s_cselect_b32 s1, 1.0, 0
	v_lshlrev_b32_e32 v140, 16, v72
	v_and_b32_e32 v141, 0xffff0000, v72
	v_lshlrev_b32_e32 v142, 16, v73
	v_and_b32_e32 v143, 0xffff0000, v73
	v_lshlrev_b32_e32 v144, 16, v74
	v_and_b32_e32 v145, 0xffff0000, v74
	v_lshlrev_b32_e32 v146, 16, v75
	v_and_b32_e32 v147, 0xffff0000, v75
	v_mov_b32_e32 v148, s1
	v_mul_f32_e32 v150, s1, v3
	v_pk_fma_f32 v[124:125], v[150:151], v[140:141], v[124:125] op_sel_hi:[0,1,1]
	v_pk_fma_f32 v[126:127], v[150:151], v[142:143], v[126:127] op_sel_hi:[0,1,1]
	v_pk_fma_f32 v[128:129], v[150:151], v[144:145], v[128:129] op_sel_hi:[0,1,1]
	v_pk_fma_f32 v[130:131], v[150:151], v[146:147], v[130:131] op_sel_hi:[0,1,1]
	v_pk_fma_f32 v[132:133], v[150:151], v[140:141], v[132:133] op_sel_hi:[0,1,1]
	v_pk_fma_f32 v[134:135], v[150:151], v[142:143], v[134:135] op_sel_hi:[0,1,1]
	v_pk_fma_f32 v[136:137], v[150:151], v[144:145], v[136:137] op_sel_hi:[0,1,1]
	v_pk_fma_f32 v[138:139], v[150:151], v[146:147], v[138:139] op_sel_hi:[0,1,1]
	s_waitcnt vmcnt(7)
	s_add_i32 s0, s24, 10
	s_cmp_lt_u32 s0, s25
	s_cselect_b32 s1, 1.0, 0
	v_lshlrev_b32_e32 v140, 16, v76
	v_and_b32_e32 v141, 0xffff0000, v76
	v_lshlrev_b32_e32 v142, 16, v77
	v_and_b32_e32 v143, 0xffff0000, v77
	v_lshlrev_b32_e32 v144, 16, v78
	v_and_b32_e32 v145, 0xffff0000, v78
	v_lshlrev_b32_e32 v146, 16, v79
	v_and_b32_e32 v147, 0xffff0000, v79
	v_mov_b32_e32 v148, s1
	v_mul_f32_e32 v150, s1, v3
	v_pk_fma_f32 v[132:133], v[150:151], v[140:141], v[132:133] op_sel_hi:[0,1,1]
	v_pk_fma_f32 v[134:135], v[150:151], v[142:143], v[134:135] op_sel_hi:[0,1,1]
	v_pk_fma_f32 v[136:137], v[150:151], v[144:145], v[136:137] op_sel_hi:[0,1,1]
	v_pk_fma_f32 v[138:139], v[150:151], v[146:147], v[138:139] op_sel_hi:[0,1,1]
	v_lshlrev_b32_e32 v164, 16, v36
	v_and_b32_e32 v165, 0xffff0000, v36
	v_lshlrev_b32_e32 v166, 16, v37
	v_and_b32_e32 v167, 0xffff0000, v37
	v_lshlrev_b32_e32 v168, 16, v38
	v_and_b32_e32 v169, 0xffff0000, v38
	v_lshlrev_b32_e32 v170, 16, v39
	v_and_b32_e32 v171, 0xffff0000, v39
	v_pk_fma_f32 v[108:109], v[152:153], v[108:109], v[164:165] op_sel_hi:[0,1,1] neg_lo:[0,0,1] neg_hi:[0,0,1]
	v_pk_fma_f32 v[110:111], v[152:153], v[110:111], v[166:167] op_sel_hi:[0,1,1] neg_lo:[0,0,1] neg_hi:[0,0,1]
	v_pk_fma_f32 v[112:113], v[152:153], v[112:113], v[168:169] op_sel_hi:[0,1,1] neg_lo:[0,0,1] neg_hi:[0,0,1]
	v_pk_fma_f32 v[114:115], v[152:153], v[114:115], v[170:171] op_sel_hi:[0,1,1] neg_lo:[0,0,1] neg_hi:[0,0,1]
	v_cvt_pk_bf16_f32 v160, v108, v109
	v_cvt_pk_bf16_f32 v161, v110, v111
	v_cvt_pk_bf16_f32 v162, v112, v113
	v_cvt_pk_bf16_f32 v163, v114, v115
	s_add_i32 s0, s22, 0
	s_lshl_b32 s0, s0, 11
	s_add_u32 s6, s16, s0
	s_addc_u32 s7, s17, 0
	global_store_dwordx4 v2, v[160:163], s[6:7] offset:1024
	v_lshlrev_b32_e32 v164, 16, v40
	v_and_b32_e32 v165, 0xffff0000, v40
	v_lshlrev_b32_e32 v166, 16, v41
	v_and_b32_e32 v167, 0xffff0000, v41
	v_lshlrev_b32_e32 v168, 16, v42
	v_and_b32_e32 v169, 0xffff0000, v42
	v_lshlrev_b32_e32 v170, 16, v43
	v_and_b32_e32 v171, 0xffff0000, v43
	v_pk_fma_f32 v[116:117], v[154:155], v[116:117], v[164:165] op_sel_hi:[0,1,1] neg_lo:[0,0,1] neg_hi:[0,0,1]
	v_pk_fma_f32 v[118:119], v[154:155], v[118:119], v[166:167] op_sel_hi:[0,1,1] neg_lo:[0,0,1] neg_hi:[0,0,1]
	v_pk_fma_f32 v[120:121], v[154:155], v[120:121], v[168:169] op_sel_hi:[0,1,1] neg_lo:[0,0,1] neg_hi:[0,0,1]
	v_pk_fma_f32 v[122:123], v[154:155], v[122:123], v[170:171] op_sel_hi:[0,1,1] neg_lo:[0,0,1] neg_hi:[0,0,1]
	v_cvt_pk_bf16_f32 v160, v116, v117
	v_cvt_pk_bf16_f32 v161, v118, v119
	v_cvt_pk_bf16_f32 v162, v120, v121
	v_cvt_pk_bf16_f32 v163, v122, v123
	s_add_i32 s0, s22, 1
	s_lshl_b32 s0, s0, 11
	s_add_u32 s6, s16, s0
	s_addc_u32 s7, s17, 0
	global_store_dwordx4 v2, v[160:163], s[6:7] offset:1024
	v_lshlrev_b32_e32 v164, 16, v44
	v_and_b32_e32 v165, 0xffff0000, v44
	v_lshlrev_b32_e32 v166, 16, v45
	v_and_b32_e32 v167, 0xffff0000, v45
	v_lshlrev_b32_e32 v168, 16, v46
	v_and_b32_e32 v169, 0xffff0000, v46
	v_lshlrev_b32_e32 v170, 16, v47
	v_and_b32_e32 v171, 0xffff0000, v47
	v_pk_fma_f32 v[124:125], v[156:157], v[124:125], v[164:165] op_sel_hi:[0,1,1] neg_lo:[0,0,1] neg_hi:[0,0,1]
	v_pk_fma_f32 v[126:127], v[156:157], v[126:127], v[166:167] op_sel_hi:[0,1,1] neg_lo:[0,0,1] neg_hi:[0,0,1]
	v_pk_fma_f32 v[128:129], v[156:157], v[128:129], v[168:169] op_sel_hi:[0,1,1] neg_lo:[0,0,1] neg_hi:[0,0,1]
	v_pk_fma_f32 v[130:131], v[156:157], v[130:131], v[170:171] op_sel_hi:[0,1,1] neg_lo:[0,0,1] neg_hi:[0,0,1]
	v_cvt_pk_bf16_f32 v160, v124, v125
	v_cvt_pk_bf16_f32 v161, v126, v127
	v_cvt_pk_bf16_f32 v162, v128, v129
	v_cvt_pk_bf16_f32 v163, v130, v131
	s_add_i32 s0, s22, 2
	s_lshl_b32 s0, s0, 11
	s_add_u32 s6, s16, s0
	s_addc_u32 s7, s17, 0
	global_store_dwordx4 v2, v[160:163], s[6:7] offset:1024
	v_lshlrev_b32_e32 v164, 16, v48
	v_and_b32_e32 v165, 0xffff0000, v48
	v_lshlrev_b32_e32 v166, 16, v49
	v_and_b32_e32 v167, 0xffff0000, v49
	v_lshlrev_b32_e32 v168, 16, v50
	v_and_b32_e32 v169, 0xffff0000, v50
	v_lshlrev_b32_e32 v170, 16, v51
	v_and_b32_e32 v171, 0xffff0000, v51
	v_pk_fma_f32 v[132:133], v[158:159], v[132:133], v[164:165] op_sel_hi:[0,1,1] neg_lo:[0,0,1] neg_hi:[0,0,1]
	v_pk_fma_f32 v[134:135], v[158:159], v[134:135], v[166:167] op_sel_hi:[0,1,1] neg_lo:[0,0,1] neg_hi:[0,0,1]
	v_pk_fma_f32 v[136:137], v[158:159], v[136:137], v[168:169] op_sel_hi:[0,1,1] neg_lo:[0,0,1] neg_hi:[0,0,1]
	v_pk_fma_f32 v[138:139], v[158:159], v[138:139], v[170:171] op_sel_hi:[0,1,1] neg_lo:[0,0,1] neg_hi:[0,0,1]
	v_cvt_pk_bf16_f32 v160, v132, v133
	v_cvt_pk_bf16_f32 v161, v134, v135
	v_cvt_pk_bf16_f32 v162, v136, v137
	v_cvt_pk_bf16_f32 v163, v138, v139
	s_add_i32 s0, s22, 3
	s_lshl_b32 s0, s0, 11
	s_add_u32 s6, s16, s0
	s_addc_u32 s7, s17, 0
	global_store_dwordx4 v2, v[160:163], s[6:7] offset:1024
	s_add_i32 s0, s24, 1
	s_min_i32 s0, s0, s25
	s_add_i32 s1, s24, -1
	s_max_i32 s1, s1, 0
	s_sub_i32 s30, s0, s1
	s_add_i32 s0, s24, 2
	s_min_i32 s0, s0, s25
	s_add_i32 s1, s24, -2
	s_max_i32 s1, s1, 0
	s_sub_i32 s31, s0, s1
	v_mov_b32_e32 v172, s30
	v_mov_b32_e32 v173, s31
	v_cndmask_b32_e64 v172, v172, v173, s[34:35]
	v_cvt_f32_u32_e32 v172, v172
	v_rcp_f32_e32 v173, v172
	s_nop 0
	v_fma_f32 v174, -v172, v173, 1.0
	v_fmac_f32_e32 v173, v174, v173
	v_mov_b32_e32 v152, v173
	s_add_i32 s0, s24, 2
	s_min_i32 s0, s0, s25
	s_add_i32 s1, s24, 0
	s_max_i32 s1, s1, 0
	s_sub_i32 s30, s0, s1
	s_add_i32 s0, s24, 3
	s_min_i32 s0, s0, s25
	s_add_i32 s1, s24, -1
	s_max_i32 s1, s1, 0
	s_sub_i32 s31, s0, s1
	v_mov_b32_e32 v172, s30
	v_mov_b32_e32 v173, s31
	v_cndmask_b32_e64 v172, v172, v173, s[34:35]
	v_cvt_f32_u32_e32 v172, v172
	v_rcp_f32_e32 v173, v172
	s_nop 0
	v_fma_f32 v174, -v172, v173, 1.0
	v_fmac_f32_e32 v173, v174, v173
	v_mov_b32_e32 v154, v173
	s_add_i32 s0, s24, 3
	s_min_i32 s0, s0, s25
	s_add_i32 s1, s24, 1
	s_max_i32 s1, s1, 0
	s_sub_i32 s30, s0, s1
	s_add_i32 s0, s24, 4
	s_min_i32 s0, s0, s25
	s_add_i32 s1, s24, 0
	s_max_i32 s1, s1, 0
	s_sub_i32 s31, s0, s1
	v_mov_b32_e32 v172, s30
	v_mov_b32_e32 v173, s31
	v_cndmask_b32_e64 v172, v172, v173, s[34:35]
	v_cvt_f32_u32_e32 v172, v172
	v_rcp_f32_e32 v173, v172
	s_nop 0
	v_fma_f32 v174, -v172, v173, 1.0
	v_fmac_f32_e32 v173, v174, v173
	v_mov_b32_e32 v156, v173
	s_add_i32 s0, s24, 4
	s_min_i32 s0, s0, s25
	s_add_i32 s1, s24, 2
	s_max_i32 s1, s1, 0
	s_sub_i32 s30, s0, s1
	s_add_i32 s0, s24, 5
	s_min_i32 s0, s0, s25
	s_add_i32 s1, s24, 1
	s_max_i32 s1, s1, 0
	s_sub_i32 s31, s0, s1
	v_mov_b32_e32 v172, s30
	v_mov_b32_e32 v173, s31
	v_cndmask_b32_e64 v172, v172, v173, s[34:35]
	v_cvt_f32_u32_e32 v172, v172
	v_rcp_f32_e32 v173, v172
	s_nop 0
	v_fma_f32 v174, -v172, v173, 1.0
	v_fmac_f32_e32 v173, v174, v173
	v_mov_b32_e32 v158, v173
	v_mov_b32_e32 v108, 0
	v_mov_b32_e32 v109, 0
	v_mov_b32_e32 v110, 0
	v_mov_b32_e32 v111, 0
	v_mov_b32_e32 v112, 0
	v_mov_b32_e32 v113, 0
	v_mov_b32_e32 v114, 0
	v_mov_b32_e32 v115, 0
	v_mov_b32_e32 v116, 0
	v_mov_b32_e32 v117, 0
	v_mov_b32_e32 v118, 0
	v_mov_b32_e32 v119, 0
	v_mov_b32_e32 v120, 0
	v_mov_b32_e32 v121, 0
	v_mov_b32_e32 v122, 0
	v_mov_b32_e32 v123, 0
	v_mov_b32_e32 v124, 0
	v_mov_b32_e32 v125, 0
	v_mov_b32_e32 v126, 0
	v_mov_b32_e32 v127, 0
	v_mov_b32_e32 v128, 0
	v_mov_b32_e32 v129, 0
	v_mov_b32_e32 v130, 0
	v_mov_b32_e32 v131, 0
	v_mov_b32_e32 v132, 0
	v_mov_b32_e32 v133, 0
	v_mov_b32_e32 v134, 0
	v_mov_b32_e32 v135, 0
	v_mov_b32_e32 v136, 0
	v_mov_b32_e32 v137, 0
	v_mov_b32_e32 v138, 0
	v_mov_b32_e32 v139, 0
	s_waitcnt vmcnt(6)
	s_add_i32 s0, s24, -2
	s_cmp_lt_u32 s0, s25
	s_cselect_b32 s1, 1.0, 0
	v_lshlrev_b32_e32 v140, 16, v80
	v_and_b32_e32 v141, 0xffff0000, v80
	v_lshlrev_b32_e32 v142, 16, v81
	v_and_b32_e32 v143, 0xffff0000, v81
	v_lshlrev_b32_e32 v144, 16, v82
	v_and_b32_e32 v145, 0xffff0000, v82
	v_lshlrev_b32_e32 v146, 16, v83
	v_and_b32_e32 v147, 0xffff0000, v83
	v_mov_b32_e32 v148, s1
	v_mul_f32_e32 v150, s1, v3
	v_pk_fma_f32 v[108:109], v[150:151], v[140:141], v[108:109] op_sel_hi:[0,1,1]
	v_pk_fma_f32 v[110:111], v[150:151], v[142:143], v[110:111] op_sel_hi:[0,1,1]
	v_pk_fma_f32 v[112:113], v[150:151], v[144:145], v[112:113] op_sel_hi:[0,1,1]
	v_pk_fma_f32 v[114:115], v[150:151], v[146:147], v[114:115] op_sel_hi:[0,1,1]
	s_waitcnt vmcnt(5)
	s_add_i32 s0, s24, -1
	s_cmp_lt_u32 s0, s25
	s_cselect_b32 s1, 1.0, 0
	v_lshlrev_b32_e32 v140, 16, v84
	v_and_b32_e32 v141, 0xffff0000, v84
	v_lshlrev_b32_e32 v142, 16, v85
	v_and_b32_e32 v143, 0xffff0000, v85
	v_lshlrev_b32_e32 v144, 16, v86
	v_and_b32_e32 v145, 0xffff0000, v86
	v_lshlrev_b32_e32 v146, 16, v87
	v_and_b32_e32 v147, 0xffff0000, v87
	v_mov_b32_e32 v148, s1
	v_mul_f32_e32 v150, s1, v3
	v_pk_fma_f32 v[108:109], v[148:149], v[140:141], v[108:109] op_sel_hi:[0,1,1]
	v_pk_fma_f32 v[110:111], v[148:149], v[142:143], v[110:111] op_sel_hi:[0,1,1]
	v_pk_fma_f32 v[112:113], v[148:149], v[144:145], v[112:113] op_sel_hi:[0,1,1]
	v_pk_fma_f32 v[114:115], v[148:149], v[146:147], v[114:115] op_sel_hi:[0,1,1]
	v_pk_fma_f32 v[116:117], v[150:151], v[140:141], v[116:117] op_sel_hi:[0,1,1]
	v_pk_fma_f32 v[118:119], v[150:151], v[142:143], v[118:119] op_sel_hi:[0,1,1]
	v_pk_fma_f32 v[120:121], v[150:151], v[144:145], v[120:121] op_sel_hi:[0,1,1]
	v_pk_fma_f32 v[122:123], v[150:151], v[146:147], v[122:123] op_sel_hi:[0,1,1]
	s_waitcnt vmcnt(4)
	s_add_i32 s0, s24, 0
	s_cmp_lt_u32 s0, s25
	s_cselect_b32 s1, 1.0, 0
	v_lshlrev_b32_e32 v140, 16, v88
	v_and_b32_e32 v141, 0xffff0000, v88
	v_lshlrev_b32_e32 v142, 16, v89
	v_and_b32_e32 v143, 0xffff0000, v89
	v_lshlrev_b32_e32 v144, 16, v90
	v_and_b32_e32 v145, 0xffff0000, v90
	v_lshlrev_b32_e32 v146, 16, v91
	v_and_b32_e32 v147, 0xffff0000, v91
	v_mov_b32_e32 v148, s1
	v_mul_f32_e32 v150, s1, v3
	v_pk_fma_f32 v[108:109], v[148:149], v[140:141], v[108:109] op_sel_hi:[0,1,1]
	v_pk_fma_f32 v[110:111], v[148:149], v[142:143], v[110:111] op_sel_hi:[0,1,1]
	v_pk_fma_f32 v[112:113], v[148:149], v[144:145], v[112:113] op_sel_hi:[0,1,1]
	v_pk_fma_f32 v[114:115], v[148:149], v[146:147], v[114:115] op_sel_hi:[0,1,1]
	v_pk_fma_f32 v[116:117], v[148:149], v[140:141], v[116:117] op_sel_hi:[0,1,1]
	v_pk_fma_f32 v[118:119], v[148:149], v[142:143], v[118:119] op_sel_hi:[0,1,1]
	v_pk_fma_f32 v[120:121], v[148:149], v[144:145], v[120:121] op_sel_hi:[0,1,1]
	v_pk_fma_f32 v[122:123], v[148:149], v[146:147], v[122:123] op_sel_hi:[0,1,1]
	v_pk_fma_f32 v[124:125], v[150:151], v[140:141], v[124:125] op_sel_hi:[0,1,1]
	v_pk_fma_f32 v[126:127], v[150:151], v[142:143], v[126:127] op_sel_hi:[0,1,1]
	v_pk_fma_f32 v[128:129], v[150:151], v[144:145], v[128:129] op_sel_hi:[0,1,1]
	v_pk_fma_f32 v[130:131], v[150:151], v[146:147], v[130:131] op_sel_hi:[0,1,1]
	s_waitcnt vmcnt(3)
	s_add_i32 s0, s24, 1
	s_cmp_lt_u32 s0, s25
	s_cselect_b32 s1, 1.0, 0
	v_lshlrev_b32_e32 v140, 16, v92
	v_and_b32_e32 v141, 0xffff0000, v92
	v_lshlrev_b32_e32 v142, 16, v93
	v_and_b32_e32 v143, 0xffff0000, v93
	v_lshlrev_b32_e32 v144, 16, v94
	v_and_b32_e32 v145, 0xffff0000, v94
	v_lshlrev_b32_e32 v146, 16, v95
	v_and_b32_e32 v147, 0xffff0000, v95
	v_mov_b32_e32 v148, s1
	v_mul_f32_e32 v150, s1, v3
	v_pk_fma_f32 v[108:109], v[150:151], v[140:141], v[108:109] op_sel_hi:[0,1,1]
	v_pk_fma_f32 v[110:111], v[150:151], v[142:143], v[110:111] op_sel_hi:[0,1,1]
	v_pk_fma_f32 v[112:113], v[150:151], v[144:145], v[112:113] op_sel_hi:[0,1,1]
	v_pk_fma_f32 v[114:115], v[150:151], v[146:147], v[114:115] op_sel_hi:[0,1,1]
	v_pk_fma_f32 v[116:117], v[148:149], v[140:141], v[116:117] op_sel_hi:[0,1,1]
	v_pk_fma_f32 v[118:119], v[148:149], v[142:143], v[118:119] op_sel_hi:[0,1,1]
	v_pk_fma_f32 v[120:121], v[148:149], v[144:145], v[120:121] op_sel_hi:[0,1,1]
	v_pk_fma_f32 v[122:123], v[148:149], v[146:147], v[122:123] op_sel_hi:[0,1,1]
	v_pk_fma_f32 v[124:125], v[148:149], v[140:141], v[124:125] op_sel_hi:[0,1,1]
	v_pk_fma_f32 v[126:127], v[148:149], v[142:143], v[126:127] op_sel_hi:[0,1,1]
	v_pk_fma_f32 v[128:129], v[148:149], v[144:145], v[128:129] op_sel_hi:[0,1,1]
	v_pk_fma_f32 v[130:131], v[148:149], v[146:147], v[130:131] op_sel_hi:[0,1,1]
	v_pk_fma_f32 v[132:133], v[150:151], v[140:141], v[132:133] op_sel_hi:[0,1,1]
	v_pk_fma_f32 v[134:135], v[150:151], v[142:143], v[134:135] op_sel_hi:[0,1,1]
	v_pk_fma_f32 v[136:137], v[150:151], v[144:145], v[136:137] op_sel_hi:[0,1,1]
	v_pk_fma_f32 v[138:139], v[150:151], v[146:147], v[138:139] op_sel_hi:[0,1,1]
	s_waitcnt vmcnt(2)
	s_add_i32 s0, s24, 2
	s_cmp_lt_u32 s0, s25
	s_cselect_b32 s1, 1.0, 0
	v_lshlrev_b32_e32 v140, 16, v96
	v_and_b32_e32 v141, 0xffff0000, v96
	v_lshlrev_b32_e32 v142, 16, v97
	v_and_b32_e32 v143, 0xffff0000, v97
	v_lshlrev_b32_e32 v144, 16, v98
	v_and_b32_e32 v145, 0xffff0000, v98
	v_lshlrev_b32_e32 v146, 16, v99
	v_and_b32_e32 v147, 0xffff0000, v99
	v_mov_b32_e32 v148, s1
	v_mul_f32_e32 v150, s1, v3
	v_pk_fma_f32 v[116:117], v[150:151], v[140:141], v[116:117] op_sel_hi:[0,1,1]
	v_pk_fma_f32 v[118:119], v[150:151], v[142:143], v[118:119] op_sel_hi:[0,1,1]
	v_pk_fma_f32 v[120:121], v[150:151], v[144:145], v[120:121] op_sel_hi:[0,1,1]
	v_pk_fma_f32 v[122:123], v[150:151], v[146:147], v[122:123] op_sel_hi:[0,1,1]
	v_pk_fma_f32 v[124:125], v[148:149], v[140:141], v[124:125] op_sel_hi:[0,1,1]
	v_pk_fma_f32 v[126:127], v[148:149], v[142:143], v[126:127] op_sel_hi:[0,1,1]
	v_pk_fma_f32 v[128:129], v[148:149], v[144:145], v[128:129] op_sel_hi:[0,1,1]
	v_pk_fma_f32 v[130:131], v[148:149], v[146:147], v[130:131] op_sel_hi:[0,1,1]
	v_pk_fma_f32 v[132:133], v[148:149], v[140:141], v[132:133] op_sel_hi:[0,1,1]
	v_pk_fma_f32 v[134:135], v[148:149], v[142:143], v[134:135] op_sel_hi:[0,1,1]
	v_pk_fma_f32 v[136:137], v[148:149], v[144:145], v[136:137] op_sel_hi:[0,1,1]
	v_pk_fma_f32 v[138:139], v[148:149], v[146:147], v[138:139] op_sel_hi:[0,1,1]
	s_waitcnt vmcnt(1)
	s_add_i32 s0, s24, 3
	s_cmp_lt_u32 s0, s25
	s_cselect_b32 s1, 1.0, 0
	v_lshlrev_b32_e32 v140, 16, v100
	v_and_b32_e32 v141, 0xffff0000, v100
	v_lshlrev_b32_e32 v142, 16, v101
	v_and_b32_e32 v143, 0xffff0000, v101
	v_lshlrev_b32_e32 v144, 16, v102
	v_and_b32_e32 v145, 0xffff0000, v102
	v_lshlrev_b32_e32 v146, 16, v103
	v_and_b32_e32 v147, 0xffff0000, v103
	v_mov_b32_e32 v148, s1
	v_mul_f32_e32 v150, s1, v3
	v_pk_fma_f32 v[124:125], v[150:151], v[140:141], v[124:125] op_sel_hi:[0,1,1]
	v_pk_fma_f32 v[126:127], v[150:151], v[142:143], v[126:127] op_sel_hi:[0,1,1]
	v_pk_fma_f32 v[128:129], v[150:151], v[144:145], v[128:129] op_sel_hi:[0,1,1]
	v_pk_fma_f32 v[130:131], v[150:151], v[146:147], v[130:131] op_sel_hi:[0,1,1]
	v_pk_fma_f32 v[132:133], v[148:149], v[140:141], v[132:133] op_sel_hi:[0,1,1]
	v_pk_fma_f32 v[134:135], v[148:149], v[142:143], v[134:135] op_sel_hi:[0,1,1]
	v_pk_fma_f32 v[136:137], v[148:149], v[144:145], v[136:137] op_sel_hi:[0,1,1]
	v_pk_fma_f32 v[138:139], v[148:149], v[146:147], v[138:139] op_sel_hi:[0,1,1]
	s_waitcnt vmcnt(0)
	s_add_i32 s0, s24, 4
	s_cmp_lt_u32 s0, s25
	s_cselect_b32 s1, 1.0, 0
	v_lshlrev_b32_e32 v140, 16, v104
	v_and_b32_e32 v141, 0xffff0000, v104
	v_lshlrev_b32_e32 v142, 16, v105
	v_and_b32_e32 v143, 0xffff0000, v105
	v_lshlrev_b32_e32 v144, 16, v106
	v_and_b32_e32 v145, 0xffff0000, v106
	v_lshlrev_b32_e32 v146, 16, v107
	v_and_b32_e32 v147, 0xffff0000, v107
	v_mov_b32_e32 v148, s1
	v_mul_f32_e32 v150, s1, v3
	v_pk_fma_f32 v[132:133], v[150:151], v[140:141], v[132:133] op_sel_hi:[0,1,1]
	v_pk_fma_f32 v[134:135], v[150:151], v[142:143], v[134:135] op_sel_hi:[0,1,1]
	v_pk_fma_f32 v[136:137], v[150:151], v[144:145], v[136:137] op_sel_hi:[0,1,1]
	v_pk_fma_f32 v[138:139], v[150:151], v[146:147], v[138:139] op_sel_hi:[0,1,1]
	v_lshlrev_b32_e32 v164, 16, v88
	v_and_b32_e32 v165, 0xffff0000, v88
	v_lshlrev_b32_e32 v166, 16, v89
	v_and_b32_e32 v167, 0xffff0000, v89
	v_lshlrev_b32_e32 v168, 16, v90
	v_and_b32_e32 v169, 0xffff0000, v90
	v_lshlrev_b32_e32 v170, 16, v91
	v_and_b32_e32 v171, 0xffff0000, v91
	v_pk_fma_f32 v[108:109], v[152:153], v[108:109], v[164:165] op_sel_hi:[0,1,1] neg_lo:[0,0,1] neg_hi:[0,0,1]
	v_pk_fma_f32 v[110:111], v[152:153], v[110:111], v[166:167] op_sel_hi:[0,1,1] neg_lo:[0,0,1] neg_hi:[0,0,1]
	v_pk_fma_f32 v[112:113], v[152:153], v[112:113], v[168:169] op_sel_hi:[0,1,1] neg_lo:[0,0,1] neg_hi:[0,0,1]
	v_pk_fma_f32 v[114:115], v[152:153], v[114:115], v[170:171] op_sel_hi:[0,1,1] neg_lo:[0,0,1] neg_hi:[0,0,1]
	v_cvt_pk_bf16_f32 v160, v108, v109
	v_cvt_pk_bf16_f32 v161, v110, v111
	v_cvt_pk_bf16_f32 v162, v112, v113
	v_cvt_pk_bf16_f32 v163, v114, v115
	s_add_i32 s0, s22, 0
	s_lshl_b32 s0, s0, 11
	s_add_u32 s6, s16, s0
	s_addc_u32 s7, s17, 0
	global_store_dwordx4 v2, v[160:163], s[6:7]
	v_lshlrev_b32_e32 v164, 16, v92
	v_and_b32_e32 v165, 0xffff0000, v92
	v_lshlrev_b32_e32 v166, 16, v93
	v_and_b32_e32 v167, 0xffff0000, v93
	v_lshlrev_b32_e32 v168, 16, v94
	v_and_b32_e32 v169, 0xffff0000, v94
	v_lshlrev_b32_e32 v170, 16, v95
	v_and_b32_e32 v171, 0xffff0000, v95
	v_pk_fma_f32 v[116:117], v[154:155], v[116:117], v[164:165] op_sel_hi:[0,1,1] neg_lo:[0,0,1] neg_hi:[0,0,1]
	v_pk_fma_f32 v[118:119], v[154:155], v[118:119], v[166:167] op_sel_hi:[0,1,1] neg_lo:[0,0,1] neg_hi:[0,0,1]
	v_pk_fma_f32 v[120:121], v[154:155], v[120:121], v[168:169] op_sel_hi:[0,1,1] neg_lo:[0,0,1] neg_hi:[0,0,1]
	v_pk_fma_f32 v[122:123], v[154:155], v[122:123], v[170:171] op_sel_hi:[0,1,1] neg_lo:[0,0,1] neg_hi:[0,0,1]
	v_cvt_pk_bf16_f32 v160, v116, v117
	v_cvt_pk_bf16_f32 v161, v118, v119
	v_cvt_pk_bf16_f32 v162, v120, v121
	v_cvt_pk_bf16_f32 v163, v122, v123
	s_add_i32 s0, s22, 1
	s_lshl_b32 s0, s0, 11
	s_add_u32 s6, s16, s0
	s_addc_u32 s7, s17, 0
	global_store_dwordx4 v2, v[160:163], s[6:7]
	v_lshlrev_b32_e32 v164, 16, v96
	v_and_b32_e32 v165, 0xffff0000, v96
	v_lshlrev_b32_e32 v166, 16, v97
	v_and_b32_e32 v167, 0xffff0000, v97
	v_lshlrev_b32_e32 v168, 16, v98
	v_and_b32_e32 v169, 0xffff0000, v98
	v_lshlrev_b32_e32 v170, 16, v99
	v_and_b32_e32 v171, 0xffff0000, v99
	v_pk_fma_f32 v[124:125], v[156:157], v[124:125], v[164:165] op_sel_hi:[0,1,1] neg_lo:[0,0,1] neg_hi:[0,0,1]
	v_pk_fma_f32 v[126:127], v[156:157], v[126:127], v[166:167] op_sel_hi:[0,1,1] neg_lo:[0,0,1] neg_hi:[0,0,1]
	v_pk_fma_f32 v[128:129], v[156:157], v[128:129], v[168:169] op_sel_hi:[0,1,1] neg_lo:[0,0,1] neg_hi:[0,0,1]
	v_pk_fma_f32 v[130:131], v[156:157], v[130:131], v[170:171] op_sel_hi:[0,1,1] neg_lo:[0,0,1] neg_hi:[0,0,1]
	v_cvt_pk_bf16_f32 v160, v124, v125
	v_cvt_pk_bf16_f32 v161, v126, v127
	v_cvt_pk_bf16_f32 v162, v128, v129
	v_cvt_pk_bf16_f32 v163, v130, v131
	s_add_i32 s0, s22, 2
	s_lshl_b32 s0, s0, 11
	s_add_u32 s6, s16, s0
	s_addc_u32 s7, s17, 0
	global_store_dwordx4 v2, v[160:163], s[6:7]
	v_lshlrev_b32_e32 v164, 16, v100
	v_and_b32_e32 v165, 0xffff0000, v100
	v_lshlrev_b32_e32 v166, 16, v101
	v_and_b32_e32 v167, 0xffff0000, v101
	v_lshlrev_b32_e32 v168, 16, v102
	v_and_b32_e32 v169, 0xffff0000, v102
	v_lshlrev_b32_e32 v170, 16, v103
	v_and_b32_e32 v171, 0xffff0000, v103
	v_pk_fma_f32 v[132:133], v[158:159], v[132:133], v[164:165] op_sel_hi:[0,1,1] neg_lo:[0,0,1] neg_hi:[0,0,1]
	v_pk_fma_f32 v[134:135], v[158:159], v[134:135], v[166:167] op_sel_hi:[0,1,1] neg_lo:[0,0,1] neg_hi:[0,0,1]
	v_pk_fma_f32 v[136:137], v[158:159], v[136:137], v[168:169] op_sel_hi:[0,1,1] neg_lo:[0,0,1] neg_hi:[0,0,1]
	v_pk_fma_f32 v[138:139], v[158:159], v[138:139], v[170:171] op_sel_hi:[0,1,1] neg_lo:[0,0,1] neg_hi:[0,0,1]
	v_cvt_pk_bf16_f32 v160, v132, v133
	v_cvt_pk_bf16_f32 v161, v134, v135
	v_cvt_pk_bf16_f32 v162, v136, v137
	v_cvt_pk_bf16_f32 v163, v138, v139
	s_add_i32 s0, s22, 3
	s_lshl_b32 s0, s0, 11
	s_add_u32 s6, s16, s0
	s_addc_u32 s7, s17, 0
	global_store_dwordx4 v2, v[160:163], s[6:7]
	s_add_i32 s8, s8, s84
	s_cmpk_lt_i32 s8, 0x2800
	s_cbranch_scc1 .Lpool_blk
	s_waitcnt vmcnt(0)
